# MLA fast loop with exp/row-sum interleaved into PV MFMA gaps; NA bias lookups batched (32 serialized LDS reads -> 2 batches + cndmask)
# speedup vs baseline: 1.0127x; 1.0127x over previous
; #define LAS __attribute__((address_space(3)))
; template <int DQ>
; DI void attn_item(const Frame& F, const AttnItem& it, const LAS float* rpb_lds) {
;     ...
;         if (it.mode == 1 && ti < it.ntl) {
;             const int krow = it.t0 + ti;
;             const LAS float* bp = rpb_lds + it.hn * 465 + (krow - r + 7) * 31 - wq + 15;
; #pragma unroll
;             for (int blk = 0; blk < 2; ++blk)
; #pragma unroll
;                 for (int i = 0; i < 16; ++i) { const int kc = 32 * blk + (i & 3) + 4 * ((i >> 2) & 1) + 8 * hh + 16 * (i >> 3); const bool ok = kc >= cs && kc < cs + 16;
;                     const int kcc = ok ? kc : cs; s[blk][i] = ok ? s[blk][i] + bp[kcc] : -INFINITY; }
;         }
.LBB0_1254:
	s_and_b64 vcc, exec, s[0:1]
	s_cbranch_vccnz .LBB0_1320
	v_add_u32_e32 v0, 0, v211
	v_add_u32_e32 v4, 0x1c3a0, v0
	v_mov_b32_e32 v183, 0xff800000
	ds_read_b32 v112, v4 offset:0
	ds_read_b32 v113, v4 offset:4
	ds_read_b32 v114, v4 offset:8
	ds_read_b32 v115, v4 offset:12
	ds_read_b32 v116, v4 offset:16
	ds_read_b32 v117, v4 offset:20
	ds_read_b32 v118, v4 offset:24
	ds_read_b32 v119, v4 offset:28
	ds_read_b32 v120, v4 offset:64
	ds_read_b32 v121, v4 offset:68
	ds_read_b32 v122, v4 offset:72
	ds_read_b32 v123, v4 offset:76
	ds_read_b32 v124, v4 offset:80
	ds_read_b32 v125, v4 offset:84
	ds_read_b32 v126, v4 offset:88
	ds_read_b32 v127, v4 offset:92
	s_waitcnt lgkmcnt(0)
	v_add_f32_e32 v112, v96, v112
	ds_read_b32 v96, v4 offset:128
	v_add_f32_e32 v113, v97, v113
	ds_read_b32 v97, v4 offset:132
	v_add_f32_e32 v114, v98, v114
	ds_read_b32 v98, v4 offset:136
	v_add_f32_e32 v115, v99, v115
	ds_read_b32 v99, v4 offset:140
	v_add_f32_e32 v116, v100, v116
	ds_read_b32 v100, v4 offset:144
	v_add_f32_e32 v117, v101, v117
	ds_read_b32 v101, v4 offset:148
	v_add_f32_e32 v118, v102, v118
	ds_read_b32 v102, v4 offset:152
	v_add_f32_e32 v119, v103, v119
	ds_read_b32 v103, v4 offset:156
	v_add_f32_e32 v120, v104, v120
	ds_read_b32 v104, v4 offset:192
	v_add_f32_e32 v121, v105, v121
	ds_read_b32 v105, v4 offset:196
	v_add_f32_e32 v122, v106, v122
	ds_read_b32 v106, v4 offset:200
	v_add_f32_e32 v123, v107, v123
	ds_read_b32 v107, v4 offset:204
	v_add_f32_e32 v124, v108, v124
	ds_read_b32 v108, v4 offset:208
	v_add_f32_e32 v125, v109, v125
	ds_read_b32 v109, v4 offset:212
	v_add_f32_e32 v126, v110, v126
	ds_read_b32 v110, v4 offset:216
	v_add_f32_e32 v127, v111, v127
	ds_read_b32 v111, v4 offset:220
	v_cndmask_b32_e64 v112, v183, v112, s[4:5]
	v_cndmask_b32_e64 v113, v183, v113, s[6:7]
	v_cndmask_b32_e64 v114, v183, v114, s[8:9]
	v_cndmask_b32_e64 v115, v183, v115, s[10:11]
	v_cndmask_b32_e64 v116, v183, v116, s[12:13]
	v_cndmask_b32_e64 v117, v183, v117, s[14:15]
	v_cndmask_b32_e64 v118, v183, v118, s[16:17]
	v_cndmask_b32_e64 v119, v183, v119, s[18:19]
	v_cndmask_b32_e64 v120, v183, v120, s[54:55]
	v_cndmask_b32_e64 v121, v183, v121, s[56:57]
	v_cndmask_b32_e64 v122, v183, v122, s[58:59]
	v_cndmask_b32_e64 v123, v183, v123, s[60:61]
	v_cndmask_b32_e64 v124, v183, v124, s[70:71]
	v_cndmask_b32_e64 v125, v183, v125, s[74:75]
	v_cndmask_b32_e64 v126, v183, v126, s[86:87]
	v_cndmask_b32_e64 v127, v183, v127, s[50:51]
	s_waitcnt lgkmcnt(0)
	v_add_f32_e32 v96, v80, v96
	v_add_f32_e32 v97, v81, v97
	v_add_f32_e32 v98, v82, v98
	v_add_f32_e32 v99, v83, v99
	v_add_f32_e32 v100, v84, v100
	v_add_f32_e32 v101, v85, v101
	v_add_f32_e32 v102, v86, v102
	v_add_f32_e32 v103, v87, v103
	v_add_f32_e32 v104, v88, v104
	v_add_f32_e32 v105, v89, v105
	v_add_f32_e32 v106, v90, v106
	v_add_f32_e32 v107, v91, v107
	v_add_f32_e32 v108, v92, v108
	v_add_f32_e32 v109, v93, v109
	v_add_f32_e32 v110, v94, v110
	v_add_f32_e32 v111, v95, v111
	v_cndmask_b32_e64 v96, v183, v96, s[92:93]
	v_cndmask_b32_e64 v97, v183, v97, s[94:95]
	v_cndmask_b32_e64 v98, v183, v98, s[96:97]
	v_cndmask_b32_e64 v99, v183, v99, s[42:43]
	v_cndmask_b32_e64 v100, v183, v100, s[76:77]
	v_cndmask_b32_e64 v101, v183, v101, s[78:79]
	v_cndmask_b32_e64 v102, v183, v102, s[80:81]
	v_cndmask_b32_e64 v103, v183, v103, s[82:83]
	v_cndmask_b32_e64 v104, v183, v104, s[20:21]
	v_cndmask_b32_e64 v105, v183, v105, s[22:23]
	v_cndmask_b32_e64 v106, v183, v106, s[24:25]
	v_cndmask_b32_e64 v107, v183, v107, s[26:27]
	v_cndmask_b32_e64 v108, v183, v108, s[28:29]
	v_cndmask_b32_e64 v109, v183, v109, s[30:31]
	v_cndmask_b32_e64 v110, v183, v110, s[34:35]
	v_cndmask_b32_e64 v111, v183, v111, s[36:37]
	v_mov_b64_e32 v[80:81], v[96:97]
	v_mov_b64_e32 v[82:83], v[98:99]
	v_mov_b64_e32 v[84:85], v[100:101]
	v_mov_b64_e32 v[86:87], v[102:103]
	v_mov_b64_e32 v[88:89], v[104:105]
	v_mov_b64_e32 v[90:91], v[106:107]
	v_mov_b64_e32 v[92:93], v[108:109]
	v_mov_b64_e32 v[94:95], v[110:111]
	v_mov_b64_e32 v[96:97], v[112:113]
	v_mov_b64_e32 v[98:99], v[114:115]
	v_mov_b64_e32 v[100:101], v[116:117]
	v_mov_b64_e32 v[102:103], v[118:119]
	v_mov_b64_e32 v[104:105], v[120:121]
	v_mov_b64_e32 v[106:107], v[122:123]
	v_mov_b64_e32 v[108:109], v[124:125]
	v_mov_b64_e32 v[110:111], v[126:127]

; #define LAS __attribute__((address_space(3)))
; DI unsigned pk2(float a, float b) { f32x2 v = {a, b}; bfv2 r = __builtin_convertvector(v, bfv2); return __builtin_bit_cast(unsigned, r); }
; template <int DQ>
; DI void attn_item(const Frame& F, const AttnItem& it, const LAS float* rpb_lds) {
;     ...
;     auto lstore = [&](int ti) {
;         LAS unsigned char* kb = base + (ti & 1) * KBYTES; LAS unsigned char* vb = base + 2 * KBYTES + (ti % 3) * VBYTES;
; #pragma unroll
;         for (int i = 0; i < 2; ++i) { const int id = tid + i * NT; *(LAS u32x4*)(kb + ((id >> 4) * KP + (id & 15) * 8) * 2) = rk[i];
;             *(LAS u32x4*)(vb + ((id >> 3) * VP + (id & 7) * 8) * 2) = rv[i]; }
;         if (DQ == 192) *(LAS u32x4*)(kb + ((tid >> 3) * KP + 128 + (tid & 7) * 8) * 2) = rr;
;     ...
;             for (int i = 0; i < 16; ++i) { const float p = __builtin_amdgcn_exp2f(s[blk][i] - mnew); s[blk][i] = p; ps += p; }
;         lrun = lrun * alpha + ps;
;         if (__builtin_amdgcn_ballot_w64(alpha != 1.f) != 0ull) {
; #pragma unroll
;             for (int db = 0; db < 4; ++db)
; #pragma unroll
;                 for (int i = 0; i < 16; ++i) o[db][i] *= alpha;
;         }
;         LAS unsigned char* vq = vb + (qq * VP + 8 * hh) * 2;
;         auto vload = [&](int step, int db) { return *(const LAS bf16x8*)(vq + (32 * db * VP + 16 * step) * 2); };
;         bf16x8 vf[2][4];
; #pragma unroll
;         for (int db = 0; db < 4; ++db) vf[0][db] = vload(0, db);
; #pragma unroll
;         for (int st = 0; st < 4; ++st) {
;             if (st + 1 < 4) {
; #pragma unroll
;                 for (int db = 0; db < 4; ++db) vf[(st + 1) & 1][db] = vload(st + 1, db); }
;             __builtin_amdgcn_sched_barrier(0);
;             const int blk = st >> 1, s2 = st & 1;
;             u32x4 pw; pw.x = pk2(s[blk][8 * s2], s[blk][8 * s2 + 1]); pw.y = pk2(s[blk][8 * s2 + 2], s[blk][8 * s2 + 3]);
;             pw.z = pk2(s[blk][8 * s2 + 4], s[blk][8 * s2 + 5]); pw.w = pk2(s[blk][8 * s2 + 6], s[blk][8 * s2 + 7]);
;             const bf16x8 pf = __builtin_bit_cast(bf16x8, pw);
; #pragma unroll
;             for (int db = 0; db < 4; ++db) o[db] = __builtin_amdgcn_mfma_f32_32x32x16_bf16(vf[st & 1][db], pf, o[db], 0, 0, 0);
;             __builtin_amdgcn_sched_barrier(0);
;         }
.Lfast_1355:
	s_mul_hi_u32 s6, s16, 0xaaaaaaab
	s_lshr_b32 s6, s6, 1
	s_mul_i32 s6, s6, 0xd800
	v_subrev_u32_e32 v176, s6, v215
	v_add_u32_e32 v180, 0, v176
	ds_read_b128 v[176:179], v180 offset:4608
	ds_read_b128 v[220:223], v180 offset:9216
	ds_read_b128 v[224:227], v180 offset:13824
	ds_read_b128 v[228:231], v180
	ds_read_b128 v[232:235], v180 offset:32
	ds_read_b128 v[236:239], v180 offset:4640
	ds_read_b128 v[240:243], v180 offset:9248
	ds_read_b128 v[244:247], v180 offset:13856
	v_exp_f32_e32 v96, v96
	v_exp_f32_e32 v97, v97
	v_exp_f32_e32 v98, v98
	v_exp_f32_e32 v99, v99
	v_exp_f32_e32 v100, v100
	v_exp_f32_e32 v101, v101
	v_exp_f32_e32 v102, v102
	v_exp_f32_e32 v103, v103
	v_cvt_pk_bf16_f32 v248, v96, v97
	v_cvt_pk_bf16_f32 v249, v98, v99
	v_cvt_pk_bf16_f32 v250, v100, v101
	v_cvt_pk_bf16_f32 v251, v102, v103
	s_waitcnt lgkmcnt(4)
	s_nop 0
	v_mfma_f32_32x32x16_bf16 v[64:79], v[228:231], v[248:251], v[64:79]
	v_exp_f32_e32 v104, v104
	v_exp_f32_e32 v105, v105
	v_mfma_f32_32x32x16_bf16 v[48:63], v[176:179], v[248:251], v[48:63]
	v_exp_f32_e32 v106, v106
	v_exp_f32_e32 v107, v107
	v_mfma_f32_32x32x16_bf16 v[32:47], v[220:223], v[248:251], v[32:47]
	v_exp_f32_e32 v108, v108
	v_exp_f32_e32 v109, v109
	v_mfma_f32_32x32x16_bf16 v[16:31], v[224:227], v[248:251], v[16:31]
	v_exp_f32_e32 v110, v110
	v_exp_f32_e32 v111, v111
	ds_read_b128 v[176:179], v180 offset:64
	ds_read_b128 v[220:223], v180 offset:4672
	ds_read_b128 v[224:227], v180 offset:9280
	ds_read_b128 v[228:231], v180 offset:13888
	v_cvt_pk_bf16_f32 v248, v104, v105
	v_cvt_pk_bf16_f32 v249, v106, v107
	v_cvt_pk_bf16_f32 v250, v108, v109
	v_cvt_pk_bf16_f32 v251, v110, v111
	s_waitcnt lgkmcnt(7)
	s_nop 0
	v_mfma_f32_32x32x16_bf16 v[64:79], v[232:235], v[248:251], v[64:79]
	v_exp_f32_e32 v80, v80
	v_exp_f32_e32 v81, v81
	v_add_f32_e32 v96, v97, v96
	v_add_f32_e32 v98, v99, v98
	s_waitcnt lgkmcnt(6)
	v_mfma_f32_32x32x16_bf16 v[48:63], v[236:239], v[248:251], v[48:63]
	v_exp_f32_e32 v82, v82
	v_exp_f32_e32 v83, v83
	v_add_f32_e32 v100, v101, v100
	v_add_f32_e32 v102, v103, v102
	s_waitcnt lgkmcnt(5)
	v_mfma_f32_32x32x16_bf16 v[32:47], v[240:243], v[248:251], v[32:47]
	v_exp_f32_e32 v84, v84
	v_exp_f32_e32 v85, v85
	v_add_f32_e32 v96, v98, v96
	v_add_f32_e32 v100, v102, v100
	s_waitcnt lgkmcnt(4)
	v_mfma_f32_32x32x16_bf16 v[16:31], v[244:247], v[248:251], v[16:31]
	v_exp_f32_e32 v86, v86
	v_exp_f32_e32 v87, v87
	v_add_f32_e32 v96, v100, v96
	ds_read_b128 v[232:235], v180 offset:96
	ds_read_b128 v[236:239], v180 offset:4704
	ds_read_b128 v[240:243], v180 offset:9312
	ds_read_b128 v[244:247], v180 offset:13920
	v_cvt_pk_bf16_f32 v248, v80, v81
	v_cvt_pk_bf16_f32 v249, v82, v83
	v_cvt_pk_bf16_f32 v250, v84, v85
	v_cvt_pk_bf16_f32 v251, v86, v87
	s_waitcnt lgkmcnt(7)
	s_nop 0
	v_mfma_f32_32x32x16_bf16 v[64:79], v[176:179], v[248:251], v[64:79]
	v_exp_f32_e32 v88, v88
	v_exp_f32_e32 v89, v89
	v_add_f32_e32 v104, v105, v104
	v_add_f32_e32 v106, v107, v106
	s_waitcnt lgkmcnt(6)
	v_mfma_f32_32x32x16_bf16 v[48:63], v[220:223], v[248:251], v[48:63]
	v_exp_f32_e32 v90, v90
	v_exp_f32_e32 v91, v91
	v_add_f32_e32 v108, v109, v108
	v_add_f32_e32 v110, v111, v110
	s_waitcnt lgkmcnt(5)
	v_mfma_f32_32x32x16_bf16 v[32:47], v[224:227], v[248:251], v[32:47]
	v_exp_f32_e32 v92, v92
	v_exp_f32_e32 v93, v93
	v_add_f32_e32 v104, v106, v104
	v_add_f32_e32 v108, v110, v108
	s_waitcnt lgkmcnt(4)
	v_mfma_f32_32x32x16_bf16 v[16:31], v[228:231], v[248:251], v[16:31]
	v_exp_f32_e32 v94, v94
	v_exp_f32_e32 v95, v95
	v_add_f32_e32 v104, v108, v104
	v_cvt_pk_bf16_f32 v176, v88, v89
	v_cvt_pk_bf16_f32 v177, v90, v91
	v_cvt_pk_bf16_f32 v178, v92, v93
	v_cvt_pk_bf16_f32 v179, v94, v95
	s_waitcnt lgkmcnt(3)
	s_nop 0
	v_mfma_f32_32x32x16_bf16 v[64:79], v[232:235], v[176:179], v[64:79]
	v_add_f32_e32 v80, v81, v80
	v_add_f32_e32 v82, v83, v82
	v_add_f32_e32 v84, v85, v84
	v_add_f32_e32 v86, v87, v86
	v_add_f32_e32 v88, v89, v88
	v_add_f32_e32 v90, v91, v90
	s_waitcnt lgkmcnt(2)
	v_mfma_f32_32x32x16_bf16 v[48:63], v[236:239], v[176:179], v[48:63]
	v_add_f32_e32 v92, v93, v92
	v_add_f32_e32 v94, v95, v94
	v_add_f32_e32 v80, v82, v80
	v_add_f32_e32 v84, v86, v84
	v_add_f32_e32 v88, v90, v88
	v_add_f32_e32 v92, v94, v92
	s_waitcnt lgkmcnt(1)
	v_mfma_f32_32x32x16_bf16 v[32:47], v[240:243], v[176:179], v[32:47]
	v_add_f32_e32 v80, v84, v80
	v_add_f32_e32 v88, v92, v88
	v_add_f32_e32 v96, v104, v96
	s_waitcnt lgkmcnt(0)
	v_mfma_f32_32x32x16_bf16 v[16:31], v[244:247], v[176:179], v[16:31]
	v_add_f32_e32 v80, v88, v80
	v_add_f32_e32 v96, v80, v96
	v_cndmask_b32_e64 v176, 0, 1, s[10:11]
	v_cmp_ne_u32_e64 s[6:7], 1, v176
	s_andn2_b64 vcc, exec, s[10:11]
	s_cbranch_vccnz .Lfast_1361
	s_cmp_eq_u32 s12, 1
	s_cselect_b32 s12, 0, 0x6400
	s_add_i32 s12, s12, 0
	v_add_u32_e32 v176, s12, v209
	s_waitcnt vmcnt(0)
	ds_write_b128 v176, v[164:167]
	ds_write_b128 v218, v[160:163]
	v_add_u32_e32 v160, s12, v210
	ds_write_b128 v160, v[156:159]
	ds_write_b128 v205, v[152:155]
	v_add_u32_e32 v152, s12, v211
	s_cmp_ge_u32 s18, s3
	s_mov_b64 s[12:13], -1
	ds_write_b128 v152, v[148:151]
	s_cbranch_scc0 .Lfast_1358
	s_add_i32 s12, s15, s19
	s_add_i32 s21, s12, 0xfffff000
	s_mov_b64 s[12:13], 0

; template <int DQ>
; DI void attn_item(const Frame& F, const AttnItem& it, const LAS float* rpb_lds) {
;     ...
;             for (int i = 0; i < 16; ++i) { const float p = __builtin_amdgcn_exp2f(s[blk][i] - mnew); s[blk][i] = p; ps += p; }
;         lrun = lrun * alpha + ps;
;     ...
;     for (int ti = 0; ti < ntile; ++ti) {
;         qk(ti);
;         if (grpB) { if (ti + 1 < ntile) lstore(ti + 1); if (ti + 2 < ntile) gload(ti + 2); __syncthreads(); }
;         smpv(ti);
;         if (!grpB) { if (ti + 1 < ntile) lstore(ti + 1); if (ti + 2 < ntile) gload(ti + 2); __syncthreads(); }
.Lfast_1361:
	s_add_i32 s18, s18, 1
	s_add_i32 s19, s19, 64
	s_add_i32 s17, s17, 1
	s_add_i32 s12, s20, s18
	s_add_i32 s16, s16, 1
	v_add_f32_e32 v205, v216, v96
	v_add_u32_e32 v213, 0x4800, v213
	v_add_u32_e32 v214, 0x4800, v214
	s_cmp_lg_u32 s12, 4
	v_add_u32_e32 v215, 0x4800, v215
	s_cbranch_scc0 .Lfast_exit
	v_mov_b32_e32 v216, v205
	v_mov_b32_e32 v174, 0
	s_mov_b32 s32, 0xff800000
	s_branch .Lfast_1347
